# v34 + dsa_sparse gather/query loads as global loads (LDS waits no longer wait for in-flight gathers)
# speedup vs baseline: 1.0127x; 1.0044x over previous
; template <class T> DI T* opqp(T* p) { unsigned long long v = (unsigned long long)p; asm volatile("" : "+s"(v)); return (T*)v; }
; DI int tid_of(int wave_s) { unsigned z = 0; asm volatile("" : "+s"(z)); int l = __builtin_amdgcn_mbcnt_hi(~0u, __builtin_amdgcn_mbcnt_lo(~0u, z)); return wave_s * 64 + l; }
; #define P kparams()
; DI void dsa_sparse_phase(unsigned char* lds, KParamPtr P, int wv) {
;   unsigned char* wsq = opqp(P->ws);
;   const float* tab = (const float*)(lds + LDS_TAB);
;   const int tid = tid_of(wv), lane = tid & 63, wave = tid >> 6;
;   bf16_t* gbuf = (bf16_t*)(lds + LDS_WORK + 4096 + wave * 9216);
;   unsigned short* idL = (unsigned short*)(lds + LDS_WORK + 4096 + wave * 9216 + 8704);
;   __syncthreads();
;   bf16_t* qlat = (bf16_t*)(wsq + OFF_U + U_QLAT);
;   const bf16_t* ckv = (const bf16_t*)(wsq + OFF_MISC + 12 * MiB);
;   const unsigned short* idx = (const unsigned short*)(wsq + OFF_U + U_IDX);
;   const int nw = gridDim.x * 8, gw = blockIdx.x * 8 + wave;
;   const int col = lane & 15, q4 = lane >> 4;
;   const float* tabc = tab + (8 + (col & 7)) * 128;
;   const int rk = 8 * (col >> 2) + (col & 3);
;   const int grow = lane >> 4, gc16 = lane & 15;
;   const bool dealt = (gridDim.x == 256);
;   const int g_lo = dealt ? (int)kSpStart[blockIdx.x >> 3] : 0, g_n = dealt ? (int)kSpStart[(blockIdx.x >> 3) + 1] - g_lo : 0;
;   auto qmap = [&](int qi) -> int {
;     const int w8 = qi & 7, blk = (qi >> 3) & 255, rnd = qi >> 11, x = blk & 7;
;     const int gidx = dealt ? g_lo + rnd : rnd * 32 + (blk >> 3);
;     return ((x >> 1) << 13) + (((gidx << 1) + (x & 1)) << 3) + w8;
;   };
;   const int qi_end = dealt ? gw + g_n * nw : NTOK;
;   u32x2 idn = (gw < qi_end) ? *(const u32x2*)(idx + (size_t)qmap(gw) * 256 + lane * 4) : (u32x2){0u, 0u};
.LBB0_1167:
	v_lshlrev_b32_e32 v6, 9, v2
	v_and_b32_e32 v7, 15, v2
	s_movk_i32 s2, 0x6000
	s_add_u32 s18, s6, 0x1ac00000
	v_and_or_b32 v6, v6, s2, v7
	s_addc_u32 s19, s7, 0
	v_lshl_add_u32 v6, v0, 4, v6
	s_add_u32 s4, s6, 0x16e00000
	v_ashrrev_i32_e32 v7, 31, v6
	v_and_b32_e32 v5, 63, v3
	s_addc_u32 s5, s7, 0
	v_lshlrev_b64 v[6:7], 9, v[6:7]
	v_lshl_add_u64 v[6:7], s[4:5], 0, v[6:7]
	v_lshlrev_b32_e32 v0, 3, v5
	v_lshl_add_u64 v[6:7], v[6:7], 0, v[0:1]
	global_load_dwordx2 v[96:97], v[6:7], off
	s_movk_i32 s2, 0x4000
	v_mul_lo_u32 v8, v4, s2
	v_lshlrev_b32_e32 v4, 9, v3
	v_add_u32_e32 v9, 0, v8
	v_and_b32_e32 v10, 15, v3
	v_and_b32_e32 v4, 0xe00, v4
	v_add_u32_e32 v106, 0, v4
	v_lshlrev_b32_e32 v4, 1, v3
	v_and_b32_e32 v5, 3, v3
	v_add_u32_e32 v107, v9, v0
	v_lshl_add_u64 v[90:91], s[4:5], 0, v[0:1]
	v_lshlrev_b32_e32 v0, 8, v10
	v_bfe_u32 v11, v3, 4, 2
	v_and_or_b32 v12, v4, 24, v5
	v_lshl_add_u64 v[4:5], s[6:7], 0, v[0:1]
	s_mov_b64 s[6:7], 0x12e00000
	v_lshl_add_u64 v[4:5], v[4:5], 0, s[6:7]
	v_lshlrev_b32_e32 v0, 3, v11
	v_and_b32_e32 v6, 48, v3
	v_mov_b32_e32 v7, v1
	v_cmp_gt_u32_e64 s[4:5], 8, v10
	v_lshl_add_u64 v[92:93], v[4:5], 0, v[6:7]
	v_lshlrev_b32_e32 v108, 3, v10
	v_lshl_add_u32 v109, v11, 1, v9
	v_lshl_add_u32 v3, v10, 4, v9
	v_mul_i32_i24_e32 v7, -14, v10
	v_add_u32_e32 v9, v9, v6
	v_mul_u32_u24_e32 v10, 0x880, v11
	v_lshl_add_u64 v[94:95], v[4:5], 0, v[0:1]
	v_mul_u32_u24_e32 v0, 0x110, v11
	v_mul_u32_u24_e32 v4, 0x110, v12
	v_or_b32_e32 v5, v8, v6
	v_readlane_b32 s2, v255, 10
	v_add3_u32 v110, v3, v7, v10
	s_mov_b64 s[20:21], 0
	v_add_u32_e32 v111, s2, v5
	v_add_u32_e32 v112, v3, v0
	v_add_u32_e32 v113, v9, v4
	s_branch .LBB0_1169

; DI void dsa_sparse_phase(unsigned char* lds, KParamPtr P, int wv) {
;     ...
;   for (int qi = gw; qi < qi_end; qi += nw) {
;     const int q = qmap(qi);
;     const int b = q >> 13, tq = q & (SEQ - 1);
;     asm volatile("" ::: "memory");
;     *(u32x2*)(idL + lane * 4) = idn;
;     asm volatile("" ::: "memory");
;     {
;       const int qn = qmap(qi + nw < qi_end ? qi + nw : qi);
;       idn = *(const u32x2*)(idx + (size_t)qn * 256 + lane * 4);
;     }
;     bf16x8 qf[4];
; #pragma unroll
;     for (int st = 0; st < 4; ++st) qf[st] = (col < 8) ? ldg8(qlat + (size_t)q * DM + col * 128 + st * 32 + q4 * 8) : zero8();
;     f32x4 O[8];
; #pragma unroll
;     for (int e = 0; e < 8; ++e) O[e] = (f32x4){0.f, 0.f, 0.f, 0.f};
;     float m = NEGB, l = 0.f;
;     u32x4 gr[8];
;     const unsigned cb = (unsigned)(b * SEQ) * 128u + (unsigned)gc16 * 8u;
; #pragma unroll
;     for (int i = 0; i < 8; ++i) {
;       int id = idL[grow + 4 * i]; id = id > SEQ - 1 ? SEQ - 1 : id;
;       gr[i] = *(const u32x4*)(ckv + cb + (unsigned)id * 128u);
;     }
.LBB0_1177:
	v_lshlrev_b32_e32 v5, 9, v3
	v_and_b32_e32 v3, 15, v3
	s_movk_i32 s2, 0x6000
	v_and_or_b32 v3, v5, s2, v3
	v_lshl_add_u32 v4, v4, 4, v3
	v_ashrrev_i32_e32 v5, 31, v4
	v_lshlrev_b64 v[4:5], 9, v[4:5]
	v_lshl_add_u64 v[4:5], v[90:91], 0, v[4:5]
	global_load_dwordx2 v[96:97], v[4:5], off
	v_lshlrev_b32_e32 v3, 9, v2
	v_and_b32_e32 v2, 15, v2
	v_and_or_b32 v2, v3, s2, v2
	v_lshl_add_u32 v50, v0, 4, v2
	v_ashrrev_i32_e32 v51, 31, v50
	v_lshlrev_b64 v[98:99], 11, v[50:51]
	v_lshl_add_u64 v[18:19], v[92:93], 0, v[98:99]
	v_mov_b32_e32 v2, 0
	v_mov_b32_e32 v6, 0
	v_mov_b32_e32 v7, 0
	v_mov_b32_e32 v8, 0
	v_mov_b32_e32 v9, 0
	s_and_saveexec_b64 s[8:9], s[4:5]
	s_cbranch_execz .LBB0_1179
	global_load_dwordx4 v[6:9], v[18:19], off
.LBB0_1179:
	s_or_b64 exec, exec, s[8:9]
	v_mov_b32_e32 v3, 0
	v_mov_b32_e32 v4, 0
	v_mov_b32_e32 v5, 0
	s_and_saveexec_b64 s[8:9], s[4:5]
	s_cbranch_execz .LBB0_1181
	global_load_dwordx4 v[2:5], v[18:19], off offset:64
.LBB0_1181:
	s_or_b64 exec, exec, s[8:9]
	v_mov_b32_e32 v10, 0
	v_mov_b32_e32 v14, 0
	v_mov_b32_e32 v15, 0
	v_mov_b32_e32 v16, 0
	v_mov_b32_e32 v17, 0
	s_and_saveexec_b64 s[8:9], s[4:5]
	s_cbranch_execz .LBB0_1183
	global_load_dwordx4 v[14:17], v[18:19], off offset:128
.LBB0_1183:
	s_or_b64 exec, exec, s[8:9]
	v_mov_b32_e32 v11, 0
	v_mov_b32_e32 v12, 0
	v_mov_b32_e32 v13, 0
	s_and_saveexec_b64 s[8:9], s[4:5]
	s_cbranch_execz .LBB0_1185
	global_load_dwordx4 v[10:13], v[18:19], off offset:192
.LBB0_1185:
	s_or_b64 exec, exec, s[8:9]
	v_lshlrev_b32_e32 v0, 7, v50
	s_mov_b32 s2, 0xfff00000
	v_and_or_b32 v0, v0, s2, v108
	v_lshl_add_u64 v[100:101], v[0:1], 1, s[18:19]
	ds_read_u16 v0, v109 offset:20992
	ds_read_u16 v20, v109 offset:21000
	ds_read_u16 v26, v109 offset:21008
	ds_read_u16 v28, v109 offset:21016
	ds_read_u16 v34, v109 offset:21024
	ds_read_u16 v36, v109 offset:21032
	ds_read_u16 v42, v109 offset:21040
	ds_read_u16 v44, v109 offset:21048
	s_waitcnt lgkmcnt(0)
	v_min_u16_e32 v0, 0x1fff, v0
	v_lshlrev_b32_e32 v0, 8, v0
	v_lshl_add_u64 v[18:19], v[100:101], 0, v[0:1]
	v_min_u16_e32 v0, 0x1fff, v20
	v_lshlrev_b32_e32 v0, 8, v0
	v_lshl_add_u64 v[22:23], v[100:101], 0, v[0:1]
	v_min_u16_e32 v0, 0x1fff, v26
	v_lshlrev_b32_e32 v0, 8, v0
	v_lshl_add_u64 v[26:27], v[100:101], 0, v[0:1]
	v_min_u16_e32 v0, 0x1fff, v28
	v_lshlrev_b32_e32 v0, 8, v0
	v_lshl_add_u64 v[30:31], v[100:101], 0, v[0:1]
	v_min_u16_e32 v0, 0x1fff, v34
	v_lshlrev_b32_e32 v0, 8, v0
	v_lshl_add_u64 v[34:35], v[100:101], 0, v[0:1]
	v_min_u16_e32 v0, 0x1fff, v36
	v_lshlrev_b32_e32 v0, 8, v0
	v_lshl_add_u64 v[38:39], v[100:101], 0, v[0:1]
	v_min_u16_e32 v0, 0x1fff, v42
	v_lshlrev_b32_e32 v0, 8, v0
	v_lshl_add_u64 v[42:43], v[100:101], 0, v[0:1]
	v_min_u16_e32 v0, 0x1fff, v44
	v_lshlrev_b32_e32 v0, 8, v0
	v_lshl_add_u64 v[46:47], v[100:101], 0, v[0:1]
	global_load_dwordx4 v[18:21], v[18:19], off
	s_nop 0
	global_load_dwordx4 v[22:25], v[22:23], off
	s_nop 0
	global_load_dwordx4 v[26:29], v[26:27], off
	s_nop 0
	global_load_dwordx4 v[30:33], v[30:31], off
	s_nop 0
	global_load_dwordx4 v[34:37], v[34:35], off
	s_nop 0
	global_load_dwordx4 v[38:41], v[38:39], off
	s_nop 0
	global_load_dwordx4 v[42:45], v[42:43], off
	s_nop 0
	global_load_dwordx4 v[46:49], v[46:47], off
	s_and_b64 s[6:7], exec, s[6:7]
	v_and_b32_e32 v102, 0x1fff, v50
	v_mov_b32_e32 v118, 0
	s_or_b64 s[20:21], s[6:7], s[20:21]
	v_mov_b32_e32 v103, v102
	v_mov_b32_e32 v86, 0xf149f2ca
	s_mov_b32 s22, 32
	v_mov_b32_e32 v115, v111
	v_mov_b32_e32 v78, 0
	v_mov_b32_e32 v79, v118
	v_mov_b32_e32 v80, v118
	v_mov_b32_e32 v81, v118
	v_mov_b32_e32 v74, 0
	v_mov_b32_e32 v75, v118
	v_mov_b32_e32 v76, v118
	v_mov_b32_e32 v77, v118
	v_mov_b32_e32 v70, 0
	v_mov_b32_e32 v71, v118
	v_mov_b32_e32 v72, v118
	v_mov_b32_e32 v73, v118
	v_mov_b32_e32 v66, 0
	v_mov_b32_e32 v67, v118
	v_mov_b32_e32 v68, v118
	v_mov_b32_e32 v69, v118
	v_mov_b32_e32 v62, 0
	v_mov_b32_e32 v63, v118
	v_mov_b32_e32 v64, v118
	v_mov_b32_e32 v65, v118
	v_mov_b32_e32 v58, 0
	v_mov_b32_e32 v59, v118
	v_mov_b32_e32 v60, v118
	v_mov_b32_e32 v61, v118
	v_mov_b32_e32 v50, 0
	v_mov_b32_e32 v51, v118
	v_mov_b32_e32 v52, v118
	v_mov_b32_e32 v53, v118
	v_mov_b32_e32 v54, 0
	v_mov_b32_e32 v55, v118
	v_mov_b32_e32 v56, v118
	v_mov_b32_e32 v57, v118
; #define MFMA16(a, b, c) __builtin_amdgcn_mfma_f32_16x16x32_bf16((a), (b), (c), 0, 0, 0)
; DI void dsa_sparse_phase(unsigned char* lds, KParamPtr P, int wv) {
;     ...
;     for (int ch = 0; ch < 8; ++ch) {
; #pragma unroll
;       for (int i = 0; i < 8; ++i) *(u32x4*)(gbuf + (grow + 4 * i) * 136 + gc16 * 8) = gr[i];
;       asm volatile("" ::: "memory");
;       {
;         const int cn = ch < 7 ? ch + 1 : ch;
; #pragma unroll
;         for (int i = 0; i < 8; ++i) {
;           int id = idL[cn * 32 + grow + 4 * i]; id = id > SEQ - 1 ? SEQ - 1 : id;
;           gr[i] = *(const u32x4*)(ckv + cb + (unsigned)id * 128u);
;         }
;       }
;       f32x4 a[2];
; #pragma unroll
;       for (int tl = 0; tl < 2; ++tl) {
;         f32x4 acc = (f32x4){0.f, 0.f, 0.f, 0.f};
; #pragma unroll
;         for (int st = 0; st < 4; ++st) acc = MFMA16(*(const bf16x8*)(gbuf + (rk + 4 * tl) * 136 + st * 32 + q4 * 8), qf[st], acc);
;         a[tl] = acc;
;       }
;       float mloc = NEGB;
; #pragma unroll
;       for (int tl = 0; tl < 2; ++tl)
; #pragma unroll
;         for (int j = 0; j < 4; ++j) {
;           const int id = idL[ch * 32 + 8 * q4 + 4 * tl + j];
;           const int dist = tq - id; const int dd = dist < 0 ? 0 : (dist > 127 ? 127 : dist);
;           const float tb = tabc[dd];
;           float z = fmaf(a[tl][j], C1, tb); z = dist < 0 ? NEGB : z;
;           a[tl][j] = z; mloc = fmaxf(mloc, z);
;         }
.LBB0_1186:
	s_cmpk_lg_i32 s22, 0x100
	s_waitcnt vmcnt(0) lgkmcnt(0)
	ds_write_b128 v112, v[18:21] offset:12288
	ds_write_b128 v112, v[22:25] offset:13376
	ds_write_b128 v112, v[26:29] offset:14464
	ds_write_b128 v112, v[30:33] offset:15552
	ds_write_b128 v112, v[34:37] offset:16640
	ds_write_b128 v112, v[38:41] offset:17728
	ds_write_b128 v112, v[42:45] offset:18816
	ds_write_b128 v112, v[46:49] offset:19904
	s_cselect_b32 s2, s22, 0xe0
	v_lshl_add_u32 v0, s2, 1, v109
	ds_read_u16 v18, v0 offset:20992
	ds_read_u16 v22, v0 offset:21000
	ds_read_u16 v26, v0 offset:21008
	ds_read_u16 v30, v0 offset:21016
	ds_read_u16 v34, v0 offset:21024
	ds_read_u16 v38, v0 offset:21032
	ds_read_u16 v42, v0 offset:21040
	ds_read_u16 v46, v0 offset:21048
	ds_read_b128 v[82:85], v113 offset:12288
	v_mov_b32_e32 v116, v118
	ds_read_b128 v[118:121], v113 offset:12352
	s_waitcnt lgkmcnt(9)
	v_min_u16_e32 v0, 0x1fff, v18
	v_lshlrev_b32_e32 v0, 8, v0
	v_lshl_add_u64 v[18:19], v[100:101], 0, v[0:1]
	s_waitcnt lgkmcnt(1)
	v_mfma_f32_16x16x32_bf16 v[82:85], v[82:85], v[6:9], 0
	ds_read_b128 v[122:125], v113 offset:13440
	v_min_u16_e32 v0, 0x1fff, v22
	v_lshlrev_b32_e32 v0, 8, v0
	s_waitcnt lgkmcnt(1)
	v_mfma_f32_16x16x32_bf16 v[82:85], v[118:121], v[2:5], v[82:85]
	ds_read_b128 v[118:121], v113 offset:12416
	v_lshl_add_u64 v[22:23], v[100:101], 0, v[0:1]
	v_min_u16_e32 v0, 0x1fff, v26
	v_lshlrev_b32_e32 v0, 8, v0
	v_lshl_add_u64 v[26:27], v[100:101], 0, v[0:1]
	s_waitcnt lgkmcnt(0)
	v_mfma_f32_16x16x32_bf16 v[82:85], v[118:121], v[14:17], v[82:85]
	ds_read_b128 v[118:121], v113 offset:12480
	v_min_u16_e32 v0, 0x1fff, v30
	v_lshlrev_b32_e32 v0, 8, v0
	v_lshl_add_u64 v[30:31], v[100:101], 0, v[0:1]
	s_waitcnt lgkmcnt(0)
	v_mfma_f32_16x16x32_bf16 v[82:85], v[118:121], v[10:13], v[82:85]
	ds_read_b128 v[118:121], v113 offset:13376
	v_min_u16_e32 v0, 0x1fff, v34
	v_lshlrev_b32_e32 v0, 8, v0
	s_waitcnt lgkmcnt(0)
	v_mfma_f32_16x16x32_bf16 v[118:121], v[118:121], v[6:9], 0
	v_lshl_add_u64 v[34:35], v[100:101], 0, v[0:1]
	v_min_u16_e32 v0, 0x1fff, v38
	v_lshlrev_b32_e32 v0, 8, v0
	v_mfma_f32_16x16x32_bf16 v[118:121], v[122:125], v[2:5], v[118:121]
	ds_read_b128 v[122:125], v113 offset:13504
	v_lshl_add_u64 v[38:39], v[100:101], 0, v[0:1]
	v_min_u16_e32 v0, 0x1fff, v42
	s_waitcnt lgkmcnt(0)
	v_mfma_f32_16x16x32_bf16 v[118:121], v[122:125], v[14:17], v[118:121]
	ds_read_b128 v[122:125], v113 offset:13568
	v_lshlrev_b32_e32 v0, 8, v0
	v_lshl_add_u64 v[42:43], v[100:101], 0, v[0:1]
	s_waitcnt lgkmcnt(0)
	v_mfma_f32_16x16x32_bf16 v[118:121], v[122:125], v[10:13], v[118:121]
	ds_read_b128 v[122:125], v115
	v_min_u16_e32 v0, 0x1fff, v46
	v_lshlrev_b32_e32 v0, 8, v0
	v_lshl_add_u64 v[46:47], v[100:101], 0, v[0:1]
	global_load_dwordx4 v[18:21], v[18:19], off
	s_waitcnt lgkmcnt(0)
	v_sub_u32_sdwa v0, v103, v125 dst_sel:DWORD dst_unused:UNUSED_PAD src0_sel:DWORD src1_sel:WORD_1
	v_sub_u32_sdwa v87, v102, v125 dst_sel:DWORD dst_unused:UNUSED_PAD src0_sel:DWORD src1_sel:WORD_0
	v_med3_i32 v88, v87, 0, v216
	v_med3_i32 v89, v0, 0, v216
	v_lshl_add_u32 v88, v88, 2, v106
	v_lshl_add_u32 v89, v89, 2, v106
	ds_read_b32 v88, v88 offset:4096
	ds_read_b32 v89, v89 offset:4096
	v_cmp_lt_i32_e32 vcc, -1, v0
	v_sub_u32_sdwa v117, v103, v124 dst_sel:DWORD dst_unused:UNUSED_PAD src0_sel:DWORD src1_sel:WORD_1
	global_load_dwordx4 v[22:25], v[22:23], off
	s_add_i32 s22, s22, 32
	s_waitcnt lgkmcnt(0)
	v_pk_fma_f32 v[88:89], v[120:121], s[44:45], v[88:89] op_sel_hi:[1,0,1]
	v_sub_u32_sdwa v120, v102, v124 dst_sel:DWORD dst_unused:UNUSED_PAD src0_sel:DWORD src1_sel:WORD_0
	v_cndmask_b32_e32 v0, v217, v89, vcc
	v_cmp_lt_i32_e32 vcc, -1, v87
	v_med3_i32 v89, v117, 0, v216
	v_lshl_add_u32 v89, v89, 2, v106
	v_cndmask_b32_e32 v87, v217, v88, vcc
	v_med3_i32 v88, v120, 0, v216
	v_lshl_add_u32 v88, v88, 2, v106
	ds_read_b32 v88, v88 offset:4096
	ds_read_b32 v89, v89 offset:4096
	v_cmp_lt_i32_e32 vcc, -1, v117
	v_sub_u32_sdwa v117, v103, v123 dst_sel:DWORD dst_unused:UNUSED_PAD src0_sel:DWORD src1_sel:WORD_1
	v_cmp_lt_i32_e64 s[8:9], -1, v117
	global_load_dwordx4 v[26:29], v[26:27], off
	s_waitcnt lgkmcnt(0)
	v_pk_fma_f32 v[88:89], v[118:119], s[44:45], v[88:89] op_sel_hi:[1,0,1]
	global_load_dwordx4 v[30:33], v[30:31], off
	v_cndmask_b32_e32 v118, v217, v89, vcc
	v_cmp_lt_i32_e32 vcc, -1, v120
	v_sub_u32_sdwa v120, v102, v123 dst_sel:DWORD dst_unused:UNUSED_PAD src0_sel:DWORD src1_sel:WORD_0
	v_med3_i32 v89, v117, 0, v216
	v_cndmask_b32_e32 v119, v217, v88, vcc
	v_med3_i32 v88, v120, 0, v216
	v_lshl_add_u32 v88, v88, 2, v106
	v_lshl_add_u32 v89, v89, 2, v106
	ds_read_b32 v88, v88 offset:4096
	ds_read_b32 v89, v89 offset:4096
	v_sub_u32_sdwa v117, v103, v122 dst_sel:DWORD dst_unused:UNUSED_PAD src0_sel:DWORD src1_sel:WORD_1
	v_cmp_lt_i32_e64 s[12:13], -1, v117
	v_cmp_lt_f32_e64 s[6:7], s62, v118
	v_cmp_lt_f32_e32 vcc, s62, v119
	s_waitcnt lgkmcnt(0)
	v_pk_fma_f32 v[84:85], v[84:85], s[44:45], v[88:89] op_sel_hi:[1,0,1]
	global_load_dwordx4 v[34:37], v[34:35], off
	v_cndmask_b32_e64 v88, v217, v85, s[8:9]
	v_cmp_lt_i32_e64 s[8:9], -1, v120
	v_sub_u32_sdwa v120, v102, v122 dst_sel:DWORD dst_unused:UNUSED_PAD src0_sel:DWORD src1_sel:WORD_0
	v_med3_i32 v85, v117, 0, v216
	v_cndmask_b32_e64 v89, v217, v84, s[8:9]
	v_med3_i32 v84, v120, 0, v216
	v_lshl_add_u32 v84, v84, 2, v106
	v_lshl_add_u32 v85, v85, 2, v106
	ds_read_b32 v84, v84 offset:4096
	ds_read_b32 v85, v85 offset:4096
	v_cmp_lt_f32_e64 s[10:11], s62, v88
	v_cmp_lt_f32_e64 s[8:9], s62, v89
	global_load_dwordx4 v[38:41], v[38:39], off
	v_add_u32_e32 v115, 64, v115
	s_waitcnt lgkmcnt(0)
; #define MFMA16(a, b, c) __builtin_amdgcn_mfma_f32_16x16x32_bf16((a), (b), (c), 0, 0, 0)
; DI unsigned pk2(float a, float b) { f32x2 v = {a, b}; bfx2 r = __builtin_convertvector(v, bfx2); return __builtin_bit_cast(unsigned, r); }
; DI float ex2(float x) { return __builtin_amdgcn_exp2f(x); }
; DI float red_max32(float x) { auto r = __builtin_amdgcn_permlane32_swap(__float_as_uint(x), __float_as_uint(x), false, false); return fmaxf(__uint_as_float(r[0]), __uint_as_float(r[1])); }
; DI float red_max16(float x) { auto r = __builtin_amdgcn_permlane16_swap(__float_as_uint(x), __float_as_uint(x), false, false); return fmaxf(__uint_as_float(r[0]), __uint_as_float(r[1])); }
; DI void dsa_sparse_phase(unsigned char* lds, KParamPtr P, int wv) {
;     ...
;           float z = fmaf(a[tl][j], C1, tb); z = dist < 0 ? NEGB : z;
;           a[tl][j] = z; mloc = fmaxf(mloc, z);
;         }
;       mloc = red_max16(mloc);
;       mloc = red_max32(mloc);
;       const float mn = fmaxf(m, mloc);
;       const float alpha = ex2(m - mn);
;       float ls = 0.f;
; #pragma unroll
;       for (int tl = 0; tl < 2; ++tl)
; #pragma unroll
;         for (int j = 0; j < 4; ++j) { float p = (a[tl][j] > -1e29f) ? ex2(a[tl][j] - mn) : 0.f; a[tl][j] = p; ls += p; }
;       l = l * alpha + ls; m = mn;
; #pragma unroll
;       for (int e = 0; e < 8; ++e) O[e] *= alpha;
;       u32x4 u; u.x = pk2(a[0][0], a[0][1]); u.y = pk2(a[0][2], a[0][3]); u.z = pk2(a[1][0], a[1][1]); u.w = pk2(a[1][2], a[1][3]);
;       const bf16x8 pf = __builtin_bit_cast(bf16x8, u);
; #pragma unroll
;       for (int rt = 0; rt < 8; ++rt) {
;         const bf16_t* gp = gbuf + (8 * q4) * 136 + rt * 16 + col;
;         u32x4 v;
;         v.x = (unsigned)gp[0] | ((unsigned)gp[136] << 16); v.y = (unsigned)gp[2 * 136] | ((unsigned)gp[3 * 136] << 16);
;         v.z = (unsigned)gp[4 * 136] | ((unsigned)gp[5 * 136] << 16); v.w = (unsigned)gp[6 * 136] | ((unsigned)gp[7 * 136] << 16);
;         O[rt] = MFMA16(__builtin_bit_cast(bf16x8, v), pf, O[rt]);
;       }
	v_pk_fma_f32 v[82:83], v[82:83], s[44:45], v[84:85] op_sel_hi:[1,0,1]
	global_load_dwordx4 v[42:45], v[42:43], off
	v_cndmask_b32_e64 v83, v217, v83, s[12:13]
	v_cmp_lt_i32_e64 s[12:13], -1, v120
	v_cmp_lt_f32_e64 s[14:15], s62, v83
	global_load_dwordx4 v[46:49], v[46:47], off
	v_cndmask_b32_e64 v82, v217, v82, s[12:13]
	v_max3_f32 v84, v82, s52, v83
	v_max3_f32 v84, v84, v89, v88
	v_max3_f32 v84, v84, v119, v118
	v_max3_f32 v84, v84, v87, v0
	v_mov_b32_e32 v85, v84
	s_nop 1
	v_permlane16_swap_b32_e32 v84, v85
	v_max_f32_e32 v85, v85, v85
	v_max_f32_e32 v84, v84, v84
	v_max_f32_e32 v84, v84, v85
	v_mov_b32_e32 v85, v84
	s_nop 1
	v_permlane32_swap_b32_e32 v84, v85
	v_max3_f32 v117, v86, v84, v85
	v_cmp_lt_f32_e64 s[12:13], s62, v82
	v_sub_f32_e32 v82, v82, v117
	v_sub_f32_e32 v118, v118, v117
	v_exp_f32_e32 v82, v82
	v_sub_f32_e32 v83, v83, v117
	v_exp_f32_e32 v118, v118
	v_sub_f32_e32 v84, v86, v117
	v_exp_f32_e32 v83, v83
	v_sub_f32_e32 v86, v89, v117
	v_exp_f32_e32 v86, v86
	v_sub_f32_e32 v88, v88, v117
	v_exp_f32_e32 v88, v88
	v_sub_f32_e32 v89, v119, v117
	v_cndmask_b32_e64 v82, 0, v82, s[12:13]
	v_exp_f32_e32 v89, v89
	v_cndmask_b32_e64 v119, 0, v118, s[6:7]
	v_cmp_lt_f32_e64 s[6:7], s62, v0
	v_sub_f32_e32 v0, v0, v117
	v_cndmask_b32_e64 v83, 0, v83, s[14:15]
	v_add_f32_e32 v85, 0, v82
	v_sub_f32_e32 v118, v87, v117
	v_exp_f32_e32 v0, v0
	v_add_f32_e32 v85, v83, v85
	v_cndmask_b32_e64 v86, 0, v86, s[8:9]
	v_exp_f32_e32 v118, v118
	v_cndmask_b32_e64 v88, 0, v88, s[10:11]
	v_add_f32_e32 v85, v86, v85
	v_add_f32_e32 v85, v88, v85
	v_cndmask_b32_e32 v89, 0, v89, vcc
	v_cmp_lt_f32_e32 vcc, s62, v87
	v_cndmask_b32_e64 v87, 0, v0, s[6:7]
	v_exp_f32_e32 v0, v84
	v_add_f32_e32 v84, v89, v85
	v_cndmask_b32_e32 v120, 0, v118, vcc
	v_add_f32_e32 v84, v119, v84
	v_add_f32_e32 v84, v120, v84
	v_add_f32_e32 v118, v87, v84
	v_cvt_pk_bf16_f32 v82, v82, v83
	v_cvt_pk_bf16_f32 v83, v86, v88
	v_cvt_pk_bf16_f32 v84, v89, v119
	v_cvt_pk_bf16_f32 v85, v120, v87
	v_mbcnt_lo_u32_b32 v196, -1, 0
	v_mbcnt_hi_u32_b32 v196, -1, v196
	v_and_b32_e32 v197, 15, v196
	v_lshrrev_b32_e32 v198, 2, v197
	v_mul_u32_u24_e32 v198, 0x110, v198
	v_and_b32_e32 v196, 3, v197
	v_lshl_add_u32 v198, v196, 3, v198
	v_lshlrev_b32_e32 v197, 1, v197
	v_sub_u32_e32 v198, v198, v197
	v_add_u32_e32 v198, v110, v198
	ds_read_b64_tr_b16 v[164:165], v198 offset:12288
	ds_read_b64_tr_b16 v[166:167], v198 offset:13376
	ds_read_b64_tr_b16 v[168:169], v198 offset:12320
	ds_read_b64_tr_b16 v[170:171], v198 offset:13408
	ds_read_b64_tr_b16 v[172:173], v198 offset:12352
	ds_read_b64_tr_b16 v[174:175], v198 offset:13440
	ds_read_b64_tr_b16 v[176:177], v198 offset:12384
	ds_read_b64_tr_b16 v[178:179], v198 offset:13472
	ds_read_b64_tr_b16 v[180:181], v198 offset:12416
	ds_read_b64_tr_b16 v[182:183], v198 offset:13504
	ds_read_b64_tr_b16 v[184:185], v198 offset:12448
	ds_read_b64_tr_b16 v[186:187], v198 offset:13536
	ds_read_b64_tr_b16 v[188:189], v198 offset:12480
	ds_read_b64_tr_b16 v[190:191], v198 offset:13568
	ds_read_b64_tr_b16 v[192:193], v198 offset:12512
	ds_read_b64_tr_b16 v[194:195], v198 offset:13600
	v_pk_mul_f32 v[56:57], v[56:57], v[0:1] op_sel_hi:[1,0]
	v_pk_mul_f32 v[54:55], v[54:55], v[0:1] op_sel_hi:[1,0]
	v_pk_mul_f32 v[52:53], v[52:53], v[0:1] op_sel_hi:[1,0]
	v_pk_mul_f32 v[50:51], v[50:51], v[0:1] op_sel_hi:[1,0]
	v_pk_mul_f32 v[60:61], v[60:61], v[0:1] op_sel_hi:[1,0]
	v_pk_mul_f32 v[58:59], v[58:59], v[0:1] op_sel_hi:[1,0]
	v_pk_mul_f32 v[64:65], v[64:65], v[0:1] op_sel_hi:[1,0]
	v_pk_mul_f32 v[62:63], v[62:63], v[0:1] op_sel_hi:[1,0]
	v_pk_mul_f32 v[68:69], v[68:69], v[0:1] op_sel_hi:[1,0]
	v_pk_mul_f32 v[66:67], v[66:67], v[0:1] op_sel_hi:[1,0]
	v_pk_mul_f32 v[72:73], v[72:73], v[0:1] op_sel_hi:[1,0]
	v_pk_mul_f32 v[70:71], v[70:71], v[0:1] op_sel_hi:[1,0]
	v_pk_mul_f32 v[76:77], v[76:77], v[0:1] op_sel_hi:[1,0]
	v_pk_mul_f32 v[74:75], v[74:75], v[0:1] op_sel_hi:[1,0]
	v_pk_mul_f32 v[80:81], v[80:81], v[0:1] op_sel_hi:[1,0]
	v_pk_mul_f32 v[78:79], v[78:79], v[0:1] op_sel_hi:[1,0]
	v_fmac_f32_e32 v118, v116, v0
	s_cmpk_lg_i32 s22, 0x120
	s_waitcnt lgkmcnt(14)
	v_mfma_f32_16x16x32_bf16 v[54:57], v[164:167], v[82:85], v[54:57]
	s_waitcnt lgkmcnt(12)
	v_mfma_f32_16x16x32_bf16 v[50:53], v[168:171], v[82:85], v[50:53]
	s_waitcnt lgkmcnt(10)
	v_mfma_f32_16x16x32_bf16 v[58:61], v[172:175], v[82:85], v[58:61]
	s_waitcnt lgkmcnt(8)
	v_mfma_f32_16x16x32_bf16 v[62:65], v[176:179], v[82:85], v[62:65]
	s_waitcnt lgkmcnt(6)
	v_mfma_f32_16x16x32_bf16 v[66:69], v[180:183], v[82:85], v[66:69]
	s_waitcnt lgkmcnt(4)
	v_mfma_f32_16x16x32_bf16 v[70:73], v[184:187], v[82:85], v[70:73]
	s_waitcnt lgkmcnt(2)
	v_mfma_f32_16x16x32_bf16 v[74:77], v[188:191], v[82:85], v[74:77]
	s_waitcnt lgkmcnt(0)
	v_mfma_f32_16x16x32_bf16 v[78:81], v[192:195], v[82:85], v[78:81]
	v_mov_b32_e32 v86, v117
	s_cbranch_scc1 .LBB0_1186
; DI u32x2 pk4(float a, float b, float c, float d) { u32x2 r; r.x = pk2(a, b); r.y = pk2(c, d); return r; }
; DI float red_sum32(float x) { auto r = __builtin_amdgcn_permlane32_swap(__float_as_uint(x), __float_as_uint(x), false, false); return __uint_as_float(r[0]) + __uint_as_float(r[1]); }
; DI float red_sum16(float x) { auto r = __builtin_amdgcn_permlane16_swap(__float_as_uint(x), __float_as_uint(x), false, false); return __uint_as_float(r[0]) + __uint_as_float(r[1]); }
; DI void dsa_sparse_phase(unsigned char* lds, KParamPtr P, int wv) {
;     ...
;     l = red_sum16(l);
;     l = red_sum32(l);
;     if (col < 8) {
;       const float inv = 1.f / l;
;       bf16_t* op = qlat + (size_t)q * DM + col * 128;
; #pragma unroll
;       for (int rt = 0; rt < 8; ++rt) *(u32x2*)(op + rt * 16 + 4 * q4) = pk4(O[rt][0] * inv, O[rt][1] * inv, O[rt][2] * inv, O[rt][3] * inv);
;     }
	v_mov_b32_e32 v0, v118
	s_nop 1
	v_permlane16_swap_b32_e32 v118, v0
	v_add_f32_e32 v0, v118, v0
	v_mov_b32_e32 v2, v0
	s_nop 1
	v_permlane32_swap_b32_e32 v0, v2
	s_and_saveexec_b64 s[6:7], s[4:5]
	s_cbranch_execz .LBB0_1168
	v_add_f32_e32 v0, v0, v2
	v_div_scale_f32 v2, s[8:9], v0, v0, 1.0
	v_rcp_f32_e32 v3, v2
	v_div_scale_f32 v4, vcc, 1.0, v0, 1.0
	v_fma_f32 v5, -v2, v3, 1.0
	v_fmac_f32_e32 v3, v5, v3
	v_mul_f32_e32 v5, v4, v3
	v_fma_f32 v6, -v2, v5, v4
	v_fmac_f32_e32 v5, v6, v3
	v_fma_f32 v2, -v2, v5, v4
	v_div_fmas_f32 v2, v2, v3, v5
	v_div_fixup_f32 v0, v2, v0, 1.0
	v_pk_mul_f32 v[4:5], v[54:55], v[0:1] op_sel_hi:[1,0]
	v_pk_mul_f32 v[6:7], v[56:57], v[0:1] op_sel_hi:[1,0]
	v_lshl_add_u64 v[2:3], v[94:95], 0, v[98:99]
	v_cvt_pk_bf16_f32 v4, v4, v5
	v_cvt_pk_bf16_f32 v5, v6, v7
	flat_store_dwordx2 v[2:3], v[4:5]
	v_pk_mul_f32 v[4:5], v[50:51], v[0:1] op_sel_hi:[1,0]
	v_pk_mul_f32 v[6:7], v[52:53], v[0:1] op_sel_hi:[1,0]
	v_cvt_pk_bf16_f32 v4, v4, v5
	v_cvt_pk_bf16_f32 v5, v6, v7
	flat_store_dwordx2 v[2:3], v[4:5] offset:32
	v_pk_mul_f32 v[4:5], v[58:59], v[0:1] op_sel_hi:[1,0]
	v_pk_mul_f32 v[6:7], v[60:61], v[0:1] op_sel_hi:[1,0]
	v_cvt_pk_bf16_f32 v4, v4, v5
	v_cvt_pk_bf16_f32 v5, v6, v7
	flat_store_dwordx2 v[2:3], v[4:5] offset:64
	v_pk_mul_f32 v[4:5], v[62:63], v[0:1] op_sel_hi:[1,0]
	v_pk_mul_f32 v[6:7], v[64:65], v[0:1] op_sel_hi:[1,0]
	v_cvt_pk_bf16_f32 v4, v4, v5
	v_cvt_pk_bf16_f32 v5, v6, v7
	flat_store_dwordx2 v[2:3], v[4:5] offset:96
	v_pk_mul_f32 v[4:5], v[66:67], v[0:1] op_sel_hi:[1,0]
	v_pk_mul_f32 v[6:7], v[68:69], v[0:1] op_sel_hi:[1,0]
	v_cvt_pk_bf16_f32 v4, v4, v5
	v_cvt_pk_bf16_f32 v5, v6, v7
	flat_store_dwordx2 v[2:3], v[4:5] offset:128
	v_pk_mul_f32 v[4:5], v[70:71], v[0:1] op_sel_hi:[1,0]
	v_pk_mul_f32 v[6:7], v[72:73], v[0:1] op_sel_hi:[1,0]
	v_cvt_pk_bf16_f32 v4, v4, v5
	v_cvt_pk_bf16_f32 v5, v6, v7
	flat_store_dwordx2 v[2:3], v[4:5] offset:160
	v_pk_mul_f32 v[4:5], v[74:75], v[0:1] op_sel_hi:[1,0]
	v_pk_mul_f32 v[6:7], v[76:77], v[0:1] op_sel_hi:[1,0]
	v_cvt_pk_bf16_f32 v4, v4, v5
	v_cvt_pk_bf16_f32 v5, v6, v7
	flat_store_dwordx2 v[2:3], v[4:5] offset:192
	v_pk_mul_f32 v[4:5], v[78:79], v[0:1] op_sel_hi:[1,0]
	v_pk_mul_f32 v[6:7], v[80:81], v[0:1] op_sel_hi:[1,0]
	v_cvt_pk_bf16_f32 v4, v4, v5
	v_cvt_pk_bf16_f32 v5, v6, v7
	flat_store_dwordx2 v[2:3], v[4:5] offset:224
	s_branch .LBB0_1168
